# attention tile step: 32-value row max via 16-op v_max3 tree (removed redundant canonicalize v_max)
# speedup vs baseline: 1.0007x; 1.0007x over previous
.LBB0_964:
	s_nop 10
	v_max3_f32 v0, v50, v34, v51
	v_max3_f32 v101, v35, v52, v36
	v_max3_f32 v102, v53, v37, v54
	v_max3_f32 v103, v38, v55, v39
	v_max3_f32 v0, v0, v56, v40
	v_max3_f32 v101, v101, v57, v41
	v_max3_f32 v102, v102, v58, v42
	v_max3_f32 v103, v103, v59, v43
	v_max3_f32 v0, v0, v60, v44
	v_max3_f32 v101, v101, v61, v45
	v_max3_f32 v102, v102, v62, v46
	v_max3_f32 v103, v103, v63, v47
	v_max3_f32 v0, v0, v64, v48
	v_max3_f32 v101, v101, v65, v49
	v_max3_f32 v0, v0, v102, v103
	v_max_f32_e32 v0, v0, v101
	ds_bpermute_b32 v101, v196, v0
	s_waitcnt lgkmcnt(0)
	v_max_f32_e32 v101, v101, v101
	v_max_f32_e32 v0, v0, v101
	v_add_f32_e32 v101, 0x40c00000, v100
	v_cmp_gt_f32_e32 vcc, v0, v101
	s_cbranch_vccz .LBB0_966
	v_max_f32_e32 v0, v0, v0
	v_max_f32_e32 v101, v100, v100
	v_max_f32_e32 v101, v101, v0
	v_sub_f32_e32 v0, v100, v101
	v_exp_f32_e32 v0, v0
	v_mov_b32_e32 v100, v101
	v_mul_f32_e32 v79, v79, v0
	v_pk_mul_f32 v[32:33], v[32:33], v[0:1] op_sel_hi:[1,0]
	v_pk_mul_f32 v[30:31], v[30:31], v[0:1] op_sel_hi:[1,0]
	v_pk_mul_f32 v[28:29], v[28:29], v[0:1] op_sel_hi:[1,0]
	v_pk_mul_f32 v[26:27], v[26:27], v[0:1] op_sel_hi:[1,0]
	v_pk_mul_f32 v[24:25], v[24:25], v[0:1] op_sel_hi:[1,0]
	v_pk_mul_f32 v[22:23], v[22:23], v[0:1] op_sel_hi:[1,0]
	v_pk_mul_f32 v[20:21], v[20:21], v[0:1] op_sel_hi:[1,0]
	v_pk_mul_f32 v[18:19], v[18:19], v[0:1] op_sel_hi:[1,0]
	v_pk_mul_f32 v[16:17], v[16:17], v[0:1] op_sel_hi:[1,0]
	v_pk_mul_f32 v[14:15], v[14:15], v[0:1] op_sel_hi:[1,0]
	v_pk_mul_f32 v[12:13], v[12:13], v[0:1] op_sel_hi:[1,0]
	v_pk_mul_f32 v[10:11], v[10:11], v[0:1] op_sel_hi:[1,0]
	v_pk_mul_f32 v[8:9], v[8:9], v[0:1] op_sel_hi:[1,0]
	v_pk_mul_f32 v[6:7], v[6:7], v[0:1] op_sel_hi:[1,0]
	v_pk_mul_f32 v[4:5], v[4:5], v[0:1] op_sel_hi:[1,0]
	v_pk_mul_f32 v[2:3], v[2:3], v[0:1] op_sel_hi:[1,0]

.LBB0_990:
	s_nop 10
	v_max3_f32 v0, v64, v48, v65
	v_max3_f32 v2, v49, v66, v50
	v_max3_f32 v3, v67, v51, v68
	v_max3_f32 v4, v52, v69, v53
	v_max3_f32 v0, v0, v70, v54
	v_max3_f32 v2, v2, v71, v55
	v_max3_f32 v3, v3, v72, v56
	v_max3_f32 v4, v4, v73, v57
	v_max3_f32 v0, v0, v74, v58
	v_max3_f32 v2, v2, v75, v59
	v_max3_f32 v3, v3, v76, v60
	v_max3_f32 v4, v4, v77, v61
	v_max3_f32 v0, v0, v78, v62
	v_max3_f32 v2, v2, v79, v63
	v_max3_f32 v0, v0, v3, v4
	v_max_f32_e32 v0, v0, v2
	ds_bpermute_b32 v2, v196, v0
	s_waitcnt lgkmcnt(0)
	v_max_f32_e32 v2, v2, v2
	v_max_f32_e32 v0, v0, v2
	v_add_f32_e32 v2, 0x40c00000, v245
	v_cmp_gt_f32_e32 vcc, v0, v2
	s_cbranch_vccz .LBB0_992
	v_max_f32_e32 v0, v0, v0
	v_max_f32_e32 v2, v245, v245
	v_max_f32_e32 v2, v2, v0
	v_sub_f32_e32 v0, v245, v2
	v_exp_f32_e32 v0, v0
	v_mov_b32_e32 v245, v2
	v_mul_f32_e32 v244, v244, v0
	v_pk_mul_f32 v[46:47], v[46:47], v[0:1] op_sel_hi:[1,0]
	v_pk_mul_f32 v[44:45], v[44:45], v[0:1] op_sel_hi:[1,0]
	v_pk_mul_f32 v[42:43], v[42:43], v[0:1] op_sel_hi:[1,0]
	v_pk_mul_f32 v[40:41], v[40:41], v[0:1] op_sel_hi:[1,0]
	v_pk_mul_f32 v[38:39], v[38:39], v[0:1] op_sel_hi:[1,0]
	v_pk_mul_f32 v[36:37], v[36:37], v[0:1] op_sel_hi:[1,0]
	v_pk_mul_f32 v[34:35], v[34:35], v[0:1] op_sel_hi:[1,0]
	v_pk_mul_f32 v[32:33], v[32:33], v[0:1] op_sel_hi:[1,0]
	v_pk_mul_f32 v[30:31], v[30:31], v[0:1] op_sel_hi:[1,0]
	v_pk_mul_f32 v[28:29], v[28:29], v[0:1] op_sel_hi:[1,0]
	v_pk_mul_f32 v[26:27], v[26:27], v[0:1] op_sel_hi:[1,0]
	v_pk_mul_f32 v[24:25], v[24:25], v[0:1] op_sel_hi:[1,0]
	v_pk_mul_f32 v[22:23], v[22:23], v[0:1] op_sel_hi:[1,0]
	v_pk_mul_f32 v[20:21], v[20:21], v[0:1] op_sel_hi:[1,0]
	v_pk_mul_f32 v[18:19], v[18:19], v[0:1] op_sel_hi:[1,0]
	v_pk_mul_f32 v[16:17], v[16:17], v[0:1] op_sel_hi:[1,0]
